# hand-written K-split sample-row GEMM (all 256 WGs) replacing mini_gemm tails in out-proj and FFN-down phases
# speedup vs baseline: 1.0344x; 1.0344x over previous
;     DI void elem(int row, int col, const f32x4 v) const { u32x2 w; w.x = pk2(v[0], v[1]); w.y = pk2(v[2], v[3]); *(u32x2*)(y + (size_t)row * 1024 + col) = w; }
; DI f32x4 mini_acc(const bf16_t* Arow, const bf16_t* Brow, int K) {
;     f32x4 acc = (f32x4){0.f, 0.f, 0.f, 0.f};
;     int k0 = 0;
;     for (; k0 + 512 <= K; k0 += 512) { bf16x8 a[16], b[16];
; #pragma unroll
;         for (int e = 0; e < 16; ++e) { a[e] = *(const bf16x8*)(Arow + k0 + 32 * e); b[e] = *(const bf16x8*)(Brow + k0 + 32 * e); }
; #pragma unroll
;         for (int e = 0; e < 16; ++e) acc = __builtin_amdgcn_mfma_f32_16x16x32_bf16(b[e], a[e], acc, 0, 0, 0); }
; template <class Epi>
; DI void mini_gemm(const bf16_t* A, int lda, const bf16_t* Bt, int ldb, int K, int N, int acol_per_256, const Epi& E, int bx, int G, int wave, int lane) {
;     const int fr = lane & 15, fq = lane >> 4; const int row = NP + 16 * wave + fr;
;     for (int q = bx; q < N / 16; q += G) {
;         const bf16_t* Arow = A + (size_t)row * lda + ((16 * q) >> 8) * acol_per_256 + 8 * fq;
;         const bf16_t* Brow = Bt + (size_t)(16 * q + fr) * ldb + 8 * fq;
;         const f32x4 acc = mini_acc(Arow, Brow, K);
;         E.elem(row, 16 * q + 4 * fq, acc); }
.LBB0_940:
	s_cmp_lg_u32 s78, 0x100
	s_cbranch_scc1 .Lsg_old_p6
	v_mbcnt_lo_u32_b32 v0, -1, 0
	v_mbcnt_hi_u32_b32 v0, -1, v0
	s_lshr_b32 s1, s84, 6
	s_lshr_b32 s32, s87, 2
	v_and_b32_e32 v1, 15, v0
	v_lshrrev_b32_e32 v2, 4, v0
	s_lshl_b32 s1, s1, 1
	s_add_i32 s1, s1, s32
	s_lshl_b32 s1, s1, 4
	s_add_i32 s1, s1, 0x8000
	v_add_u32_e32 v3, s1, v1
	s_and_b32 s0, s84, 63
	s_lshl_b32 s0, s0, 4
	v_add_u32_e32 v4, s0, v1
	s_and_b32 s32, s87, 3
	s_mul_i32 s32, s32, 0x200
	v_lshl_add_u32 v6, v2, 4, s32
	v_mov_b32_e32 v7, 0
	s_add_u32 s98, s90, 0x21b00000
	s_addc_u32 s99, s91, 0
	s_add_u32 s100, s90, 0x200000
	s_addc_u32 s101, s91, 0
	s_movk_i32 s2, 0x800
	v_lshl_add_u64 v[8:9], s[98:99], 0, v[6:7]
	v_lshl_add_u64 v[10:11], s[100:101], 0, v[6:7]
	v_mad_u64_u32 v[8:9], vcc, v3, s2, v[8:9]
	v_mad_u64_u32 v[10:11], vcc, v4, s2, v[10:11]
	global_load_dwordx4 v[20:23], v[8:9], off
	global_load_dwordx4 v[52:55], v[10:11], off
	global_load_dwordx4 v[24:27], v[8:9], off offset:64
	global_load_dwordx4 v[56:59], v[10:11], off offset:64
	global_load_dwordx4 v[28:31], v[8:9], off offset:128
	global_load_dwordx4 v[60:63], v[10:11], off offset:128
	global_load_dwordx4 v[32:35], v[8:9], off offset:192
	global_load_dwordx4 v[64:67], v[10:11], off offset:192
	global_load_dwordx4 v[36:39], v[8:9], off offset:256
	global_load_dwordx4 v[68:71], v[10:11], off offset:256
	global_load_dwordx4 v[40:43], v[8:9], off offset:320
	global_load_dwordx4 v[72:75], v[10:11], off offset:320
	global_load_dwordx4 v[44:47], v[8:9], off offset:384
	global_load_dwordx4 v[76:79], v[10:11], off offset:384
	global_load_dwordx4 v[48:51], v[8:9], off offset:448
	global_load_dwordx4 v[80:83], v[10:11], off offset:448
	s_lshl_b32 s1, s87, 10
	v_lshl_add_u32 v12, v0, 4, s1
	v_lshlrev_b32_e32 v14, 3, v2
	s_lshl_b32 s1, s0, 1
	v_add_u32_e32 v14, s1, v14
	v_mov_b32_e32 v15, 0
	s_add_u32 s98, s90, 0x8500000
	s_addc_u32 s99, s91, 0
	s_movk_i32 s2, 0x800
	v_lshl_add_u64 v[102:103], s[98:99], 0, v[14:15]
	v_mad_u64_u32 v[102:103], vcc, v3, s2, v[102:103]
	s_waitcnt vmcnt(14)
	v_mfma_f32_16x16x32_bf16 v[84:87], v[52:55], v[20:23], 0
	s_waitcnt vmcnt(12)
	v_mfma_f32_16x16x32_bf16 v[84:87], v[56:59], v[24:27], v[84:87]
	s_waitcnt vmcnt(10)
	v_mfma_f32_16x16x32_bf16 v[84:87], v[60:63], v[28:31], v[84:87]
	s_waitcnt vmcnt(8)
	v_mfma_f32_16x16x32_bf16 v[84:87], v[64:67], v[32:35], v[84:87]
	s_waitcnt vmcnt(6)
	v_mfma_f32_16x16x32_bf16 v[84:87], v[68:71], v[36:39], v[84:87]
	s_waitcnt vmcnt(4)
	v_mfma_f32_16x16x32_bf16 v[84:87], v[72:75], v[40:43], v[84:87]
	s_waitcnt vmcnt(2)
	v_mfma_f32_16x16x32_bf16 v[84:87], v[76:79], v[44:47], v[84:87]
	s_waitcnt vmcnt(0)
	v_mfma_f32_16x16x32_bf16 v[84:87], v[80:83], v[48:51], v[84:87]
	s_nop 7
	s_nop 1
	ds_write_b128 v12, v[84:87]
	s_waitcnt lgkmcnt(0)
	s_barrier
	s_and_b32 s32, s87, 3
	s_cmp_lg_u32 s32, 0
	s_cbranch_scc1 .Lsg_done_p6
	ds_read_b128 v[88:91], v12 offset:1024
	ds_read_b128 v[92:95], v12 offset:2048
	ds_read_b128 v[96:99], v12 offset:3072
	s_waitcnt lgkmcnt(0)
	v_pk_add_f32 v[84:85], v[84:85], v[88:89]
	v_pk_add_f32 v[86:87], v[86:87], v[90:91]
	v_pk_add_f32 v[92:93], v[92:93], v[96:97]
	v_pk_add_f32 v[94:95], v[94:95], v[98:99]
	v_pk_add_f32 v[84:85], v[84:85], v[92:93]
	v_pk_add_f32 v[86:87], v[86:87], v[94:95]
	v_cvt_pk_bf16_f32 v100, v84, v85
	v_cvt_pk_bf16_f32 v101, v86, v87
	global_store_dwordx2 v[102:103], v[100:101], off
.Lsg_done_p6:
	s_branch .LBB0_943

;     DI void elem(int row, int col, const f32x4 v) const { u32x2 w; w.x = pk2(v[0], v[1]); w.y = pk2(v[2], v[3]); *(u32x2*)(y + (size_t)row * 1024 + col) = w; }
; DI f32x4 mini_acc(const bf16_t* Arow, const bf16_t* Brow, int K) {
;     f32x4 acc = (f32x4){0.f, 0.f, 0.f, 0.f};
;     int k0 = 0;
;     for (; k0 + 512 <= K; k0 += 512) { bf16x8 a[16], b[16];
; #pragma unroll
;         for (int e = 0; e < 16; ++e) { a[e] = *(const bf16x8*)(Arow + k0 + 32 * e); b[e] = *(const bf16x8*)(Brow + k0 + 32 * e); }
; #pragma unroll
;         for (int e = 0; e < 16; ++e) acc = __builtin_amdgcn_mfma_f32_16x16x32_bf16(b[e], a[e], acc, 0, 0, 0); }
; template <class Epi>
; DI void mini_gemm(const bf16_t* A, int lda, const bf16_t* Bt, int ldb, int K, int N, int acol_per_256, const Epi& E, int bx, int G, int wave, int lane) {
;     const int fr = lane & 15, fq = lane >> 4; const int row = NP + 16 * wave + fr;
;     for (int q = bx; q < N / 16; q += G) {
;         const bf16_t* Arow = A + (size_t)row * lda + ((16 * q) >> 8) * acol_per_256 + 8 * fq;
;         const bf16_t* Brow = Bt + (size_t)(16 * q + fr) * ldb + 8 * fq;
;         const f32x4 acc = mini_acc(Arow, Brow, K);
;         E.elem(row, 16 * q + 4 * fq, acc); }
.LBB0_1132:
	s_cmp_lg_u32 s78, 0x100
	s_cbranch_scc1 .Lsg_old_p9
	v_mbcnt_lo_u32_b32 v0, -1, 0
	v_mbcnt_hi_u32_b32 v0, -1, v0
	s_lshr_b32 s1, s84, 6
	s_lshr_b32 s32, s87, 2
	v_and_b32_e32 v1, 15, v0
	v_lshrrev_b32_e32 v2, 4, v0
	s_lshl_b32 s1, s1, 1
	s_add_i32 s1, s1, s32
	s_lshl_b32 s1, s1, 4
	s_add_i32 s1, s1, 0x8000
	v_add_u32_e32 v3, s1, v1
	s_and_b32 s0, s84, 63
	s_lshl_b32 s0, s0, 4
	v_add_u32_e32 v4, s0, v1
	s_and_b32 s32, s87, 3
	s_mul_i32 s32, s32, 0x580
	v_lshl_add_u32 v6, v2, 4, s32
	v_mov_b32_e32 v7, 0
	s_add_u32 s98, s90, 0x14800000
	s_addc_u32 s99, s91, 0
	s_add_u32 s100, s90, 0x2300000
	s_addc_u32 s101, s91, 0
	s_movk_i32 s2, 0x1600
	v_lshl_add_u64 v[8:9], s[98:99], 0, v[6:7]
	v_lshl_add_u64 v[10:11], s[100:101], 0, v[6:7]
	v_mad_u64_u32 v[8:9], vcc, v3, s2, v[8:9]
	v_mad_u64_u32 v[10:11], vcc, v4, s2, v[10:11]
	global_load_dwordx4 v[20:23], v[8:9], off
	global_load_dwordx4 v[108:111], v[10:11], off
	global_load_dwordx4 v[24:27], v[8:9], off offset:64
	global_load_dwordx4 v[112:115], v[10:11], off offset:64
	global_load_dwordx4 v[28:31], v[8:9], off offset:128
	global_load_dwordx4 v[116:119], v[10:11], off offset:128
	global_load_dwordx4 v[32:35], v[8:9], off offset:192
	global_load_dwordx4 v[120:123], v[10:11], off offset:192
	global_load_dwordx4 v[36:39], v[8:9], off offset:256
	global_load_dwordx4 v[124:127], v[10:11], off offset:256
	global_load_dwordx4 v[40:43], v[8:9], off offset:320
	global_load_dwordx4 v[128:131], v[10:11], off offset:320
	global_load_dwordx4 v[44:47], v[8:9], off offset:384
	global_load_dwordx4 v[132:135], v[10:11], off offset:384
	global_load_dwordx4 v[48:51], v[8:9], off offset:448
	global_load_dwordx4 v[136:139], v[10:11], off offset:448
	global_load_dwordx4 v[52:55], v[8:9], off offset:512
	global_load_dwordx4 v[140:143], v[10:11], off offset:512
	global_load_dwordx4 v[56:59], v[8:9], off offset:576
	global_load_dwordx4 v[144:147], v[10:11], off offset:576
	global_load_dwordx4 v[60:63], v[8:9], off offset:640
	global_load_dwordx4 v[148:151], v[10:11], off offset:640
	global_load_dwordx4 v[64:67], v[8:9], off offset:704
	global_load_dwordx4 v[152:155], v[10:11], off offset:704
	global_load_dwordx4 v[68:71], v[8:9], off offset:768
	global_load_dwordx4 v[156:159], v[10:11], off offset:768
	global_load_dwordx4 v[72:75], v[8:9], off offset:832
	global_load_dwordx4 v[160:163], v[10:11], off offset:832
	global_load_dwordx4 v[76:79], v[8:9], off offset:896
	global_load_dwordx4 v[164:167], v[10:11], off offset:896
	global_load_dwordx4 v[80:83], v[8:9], off offset:960
	global_load_dwordx4 v[168:171], v[10:11], off offset:960
	global_load_dwordx4 v[84:87], v[8:9], off offset:1024
	global_load_dwordx4 v[172:175], v[10:11], off offset:1024
	global_load_dwordx4 v[88:91], v[8:9], off offset:1088
	global_load_dwordx4 v[176:179], v[10:11], off offset:1088
	global_load_dwordx4 v[92:95], v[8:9], off offset:1152
	global_load_dwordx4 v[180:183], v[10:11], off offset:1152
	global_load_dwordx4 v[96:99], v[8:9], off offset:1216
	global_load_dwordx4 v[184:187], v[10:11], off offset:1216
	global_load_dwordx4 v[100:103], v[8:9], off offset:1280
	global_load_dwordx4 v[188:191], v[10:11], off offset:1280
	global_load_dwordx4 v[104:107], v[8:9], off offset:1344
	global_load_dwordx4 v[192:195], v[10:11], off offset:1344
	s_lshl_b32 s1, s87, 10
	v_lshl_add_u32 v12, v0, 4, s1
	v_lshlrev_b32_e32 v14, 3, v2
	s_lshl_b32 s1, s0, 1
	v_add_u32_e32 v14, s1, v14
	v_mov_b32_e32 v15, 0
	s_add_u32 s98, s90, 0x8500000
	s_addc_u32 s99, s91, 0
	s_movk_i32 s2, 0x800
	v_lshl_add_u64 v[214:215], s[98:99], 0, v[14:15]
	v_mad_u64_u32 v[214:215], vcc, v3, s2, v[214:215]
	s_waitcnt vmcnt(42)
	v_mfma_f32_16x16x32_bf16 v[196:199], v[108:111], v[20:23], 0
	s_waitcnt vmcnt(40)
	v_mfma_f32_16x16x32_bf16 v[196:199], v[112:115], v[24:27], v[196:199]
	s_waitcnt vmcnt(38)
	v_mfma_f32_16x16x32_bf16 v[196:199], v[116:119], v[28:31], v[196:199]
	s_waitcnt vmcnt(36)
	v_mfma_f32_16x16x32_bf16 v[196:199], v[120:123], v[32:35], v[196:199]
	s_waitcnt vmcnt(34)
	v_mfma_f32_16x16x32_bf16 v[196:199], v[124:127], v[36:39], v[196:199]
	s_waitcnt vmcnt(32)
	v_mfma_f32_16x16x32_bf16 v[196:199], v[128:131], v[40:43], v[196:199]
	s_waitcnt vmcnt(30)
	v_mfma_f32_16x16x32_bf16 v[196:199], v[132:135], v[44:47], v[196:199]
	s_waitcnt vmcnt(28)
	v_mfma_f32_16x16x32_bf16 v[196:199], v[136:139], v[48:51], v[196:199]
	s_waitcnt vmcnt(26)
	v_mfma_f32_16x16x32_bf16 v[196:199], v[140:143], v[52:55], v[196:199]
	s_waitcnt vmcnt(24)
	v_mfma_f32_16x16x32_bf16 v[196:199], v[144:147], v[56:59], v[196:199]
	s_waitcnt vmcnt(22)
	v_mfma_f32_16x16x32_bf16 v[196:199], v[148:151], v[60:63], v[196:199]
	s_waitcnt vmcnt(20)
	v_mfma_f32_16x16x32_bf16 v[196:199], v[152:155], v[64:67], v[196:199]
	s_waitcnt vmcnt(18)
	v_mfma_f32_16x16x32_bf16 v[196:199], v[156:159], v[68:71], v[196:199]
	s_waitcnt vmcnt(16)
	v_mfma_f32_16x16x32_bf16 v[196:199], v[160:163], v[72:75], v[196:199]
	s_waitcnt vmcnt(14)
	v_mfma_f32_16x16x32_bf16 v[196:199], v[164:167], v[76:79], v[196:199]
	s_waitcnt vmcnt(12)
	v_mfma_f32_16x16x32_bf16 v[196:199], v[168:171], v[80:83], v[196:199]
	s_waitcnt vmcnt(10)
	v_mfma_f32_16x16x32_bf16 v[196:199], v[172:175], v[84:87], v[196:199]
	s_waitcnt vmcnt(8)
	v_mfma_f32_16x16x32_bf16 v[196:199], v[176:179], v[88:91], v[196:199]
	s_waitcnt vmcnt(6)
	v_mfma_f32_16x16x32_bf16 v[196:199], v[180:183], v[92:95], v[196:199]
	s_waitcnt vmcnt(4)
	v_mfma_f32_16x16x32_bf16 v[196:199], v[184:187], v[96:99], v[196:199]
	s_waitcnt vmcnt(2)
	v_mfma_f32_16x16x32_bf16 v[196:199], v[188:191], v[100:103], v[196:199]
	s_waitcnt vmcnt(0)
	v_mfma_f32_16x16x32_bf16 v[196:199], v[192:195], v[104:107], v[196:199]
	s_nop 7
	s_nop 1
	ds_write_b128 v12, v[196:199]
	s_waitcnt lgkmcnt(0)
	s_barrier
	s_and_b32 s32, s87, 3
	s_cmp_lg_u32 s32, 0
	s_cbranch_scc1 .Lsg_done_p9
	ds_read_b128 v[200:203], v12 offset:1024
	ds_read_b128 v[204:207], v12 offset:2048
	ds_read_b128 v[208:211], v12 offset:3072
	s_waitcnt lgkmcnt(0)
	v_pk_add_f32 v[196:197], v[196:197], v[200:201]
	v_pk_add_f32 v[198:199], v[198:199], v[202:203]
	v_pk_add_f32 v[204:205], v[204:205], v[208:209]
	v_pk_add_f32 v[206:207], v[206:207], v[210:211]
	v_pk_add_f32 v[196:197], v[196:197], v[204:205]
	v_pk_add_f32 v[198:199], v[198:199], v[206:207]
	v_cvt_pk_bf16_f32 v212, v196, v197
	v_cvt_pk_bf16_f32 v213, v198, v199
	global_store_dwordx2 v[214:215], v[212:213], off

;     DI void elem(int row, int col, const f32x4 v) const { u32x2 w; w.x = pk2(v[0], v[1]); w.y = pk2(v[2], v[3]); *(u32x2*)(y + (size_t)row * 1024 + col) = w; }
; DI f32x4 mini_acc(const bf16_t* Arow, const bf16_t* Brow, int K) {
;     f32x4 acc = (f32x4){0.f, 0.f, 0.f, 0.f};
;     int k0 = 0;
;     for (; k0 + 512 <= K; k0 += 512) { bf16x8 a[16], b[16];
; #pragma unroll
;         for (int e = 0; e < 16; ++e) { a[e] = *(const bf16x8*)(Arow + k0 + 32 * e); b[e] = *(const bf16x8*)(Brow + k0 + 32 * e); }
; #pragma unroll
;         for (int e = 0; e < 16; ++e) acc = __builtin_amdgcn_mfma_f32_16x16x32_bf16(b[e], a[e], acc, 0, 0, 0); }
; template <class Epi>
; DI void mini_gemm(const bf16_t* A, int lda, const bf16_t* Bt, int ldb, int K, int N, int acol_per_256, const Epi& E, int bx, int G, int wave, int lane) {
;     const int fr = lane & 15, fq = lane >> 4; const int row = NP + 16 * wave + fr;
;     for (int q = bx; q < N / 16; q += G) {
;         const bf16_t* Arow = A + (size_t)row * lda + ((16 * q) >> 8) * acol_per_256 + 8 * fq;
;         const bf16_t* Brow = Bt + (size_t)(16 * q + fr) * ldb + 8 * fq;
;         const f32x4 acc = mini_acc(Arow, Brow, K);
;         E.elem(row, 16 * q + 4 * fq, acc); }
.LBB0_1675:
	s_cmp_lg_u32 s78, 0x100
	s_cbranch_scc1 .Lsg_old_p14
	v_mbcnt_lo_u32_b32 v0, -1, 0
	v_mbcnt_hi_u32_b32 v0, -1, v0
	s_lshr_b32 s1, s84, 6
	s_lshr_b32 s32, s87, 2
	v_and_b32_e32 v1, 15, v0
	v_lshrrev_b32_e32 v2, 4, v0
	s_lshl_b32 s1, s1, 1
	s_add_i32 s1, s1, s32
	s_lshl_b32 s1, s1, 4
	s_add_i32 s1, s1, 0x8000
	v_add_u32_e32 v3, s1, v1
	s_and_b32 s0, s84, 63
	s_lshl_b32 s0, s0, 4
	v_add_u32_e32 v4, s0, v1
	s_and_b32 s32, s87, 3
	s_mul_i32 s32, s32, 0x200
	v_lshl_add_u32 v6, v2, 4, s32
	v_mov_b32_e32 v7, 0
	s_add_u32 s98, s90, 0x2cd00000
	s_addc_u32 s99, s91, 0
	s_add_u32 s100, s90, 0x500000
	s_addc_u32 s101, s91, 0
	s_movk_i32 s2, 0x800
	v_lshl_add_u64 v[8:9], s[98:99], 0, v[6:7]
	v_lshl_add_u64 v[10:11], s[100:101], 0, v[6:7]
	v_mad_u64_u32 v[8:9], vcc, v3, s2, v[8:9]
	v_mad_u64_u32 v[10:11], vcc, v4, s2, v[10:11]
	global_load_dwordx4 v[20:23], v[8:9], off
	global_load_dwordx4 v[52:55], v[10:11], off
	global_load_dwordx4 v[24:27], v[8:9], off offset:64
	global_load_dwordx4 v[56:59], v[10:11], off offset:64
	global_load_dwordx4 v[28:31], v[8:9], off offset:128
	global_load_dwordx4 v[60:63], v[10:11], off offset:128
	global_load_dwordx4 v[32:35], v[8:9], off offset:192
	global_load_dwordx4 v[64:67], v[10:11], off offset:192
	global_load_dwordx4 v[36:39], v[8:9], off offset:256
	global_load_dwordx4 v[68:71], v[10:11], off offset:256
	global_load_dwordx4 v[40:43], v[8:9], off offset:320
	global_load_dwordx4 v[72:75], v[10:11], off offset:320
	global_load_dwordx4 v[44:47], v[8:9], off offset:384
	global_load_dwordx4 v[76:79], v[10:11], off offset:384
	global_load_dwordx4 v[48:51], v[8:9], off offset:448
	global_load_dwordx4 v[80:83], v[10:11], off offset:448
	s_lshl_b32 s1, s87, 10
	v_lshl_add_u32 v12, v0, 4, s1
	v_lshlrev_b32_e32 v14, 3, v2
	s_lshl_b32 s1, s0, 1
	v_add_u32_e32 v14, s1, v14
	v_mov_b32_e32 v15, 0
	s_add_u32 s98, s90, 0x8500000
	s_addc_u32 s99, s91, 0
	s_movk_i32 s2, 0x800
	v_lshl_add_u64 v[102:103], s[98:99], 0, v[14:15]
	v_mad_u64_u32 v[102:103], vcc, v3, s2, v[102:103]
	s_waitcnt vmcnt(14)
	v_mfma_f32_16x16x32_bf16 v[84:87], v[52:55], v[20:23], 0
	s_waitcnt vmcnt(12)
	v_mfma_f32_16x16x32_bf16 v[84:87], v[56:59], v[24:27], v[84:87]
	s_waitcnt vmcnt(10)
	v_mfma_f32_16x16x32_bf16 v[84:87], v[60:63], v[28:31], v[84:87]
	s_waitcnt vmcnt(8)
	v_mfma_f32_16x16x32_bf16 v[84:87], v[64:67], v[32:35], v[84:87]
	s_waitcnt vmcnt(6)
	v_mfma_f32_16x16x32_bf16 v[84:87], v[68:71], v[36:39], v[84:87]
	s_waitcnt vmcnt(4)
	v_mfma_f32_16x16x32_bf16 v[84:87], v[72:75], v[40:43], v[84:87]
	s_waitcnt vmcnt(2)
	v_mfma_f32_16x16x32_bf16 v[84:87], v[76:79], v[44:47], v[84:87]
	s_waitcnt vmcnt(0)
	v_mfma_f32_16x16x32_bf16 v[84:87], v[80:83], v[48:51], v[84:87]
	s_nop 7
	s_nop 1
	ds_write_b128 v12, v[84:87]
	s_waitcnt lgkmcnt(0)
	s_barrier
	s_and_b32 s32, s87, 3
	s_cmp_lg_u32 s32, 0
	s_cbranch_scc1 .Lsg_done_p14
	ds_read_b128 v[88:91], v12 offset:1024
	ds_read_b128 v[92:95], v12 offset:2048
	ds_read_b128 v[96:99], v12 offset:3072
	s_waitcnt lgkmcnt(0)
	v_pk_add_f32 v[84:85], v[84:85], v[88:89]
	v_pk_add_f32 v[86:87], v[86:87], v[90:91]
	v_pk_add_f32 v[92:93], v[92:93], v[96:97]
	v_pk_add_f32 v[94:95], v[94:95], v[98:99]
	v_pk_add_f32 v[84:85], v[84:85], v[92:93]
	v_pk_add_f32 v[86:87], v[86:87], v[94:95]
	v_cvt_pk_bf16_f32 v100, v84, v85
	v_cvt_pk_bf16_f32 v101, v86, v87
	global_store_dwordx2 v[102:103], v[100:101], off

;     DI void elem(int row, int col, const f32x4 v) const { u32x2 w; w.x = pk2(v[0], v[1]); w.y = pk2(v[2], v[3]); *(u32x2*)(y + (size_t)row * 1024 + col) = w; }
; DI f32x4 mini_acc(const bf16_t* Arow, const bf16_t* Brow, int K) {
;     f32x4 acc = (f32x4){0.f, 0.f, 0.f, 0.f};
;     int k0 = 0;
;     for (; k0 + 512 <= K; k0 += 512) { bf16x8 a[16], b[16];
; #pragma unroll
;         for (int e = 0; e < 16; ++e) { a[e] = *(const bf16x8*)(Arow + k0 + 32 * e); b[e] = *(const bf16x8*)(Brow + k0 + 32 * e); }
; #pragma unroll
;         for (int e = 0; e < 16; ++e) acc = __builtin_amdgcn_mfma_f32_16x16x32_bf16(b[e], a[e], acc, 0, 0, 0); }
; template <class Epi>
; DI void mini_gemm(const bf16_t* A, int lda, const bf16_t* Bt, int ldb, int K, int N, int acol_per_256, const Epi& E, int bx, int G, int wave, int lane) {
;     const int fr = lane & 15, fq = lane >> 4; const int row = NP + 16 * wave + fr;
;     for (int q = bx; q < N / 16; q += G) {
;         const bf16_t* Arow = A + (size_t)row * lda + ((16 * q) >> 8) * acol_per_256 + 8 * fq;
;         const bf16_t* Brow = Bt + (size_t)(16 * q + fr) * ldb + 8 * fq;
;         const f32x4 acc = mini_acc(Arow, Brow, K);
;         E.elem(row, 16 * q + 4 * fq, acc); }
.LBB0_1867:
	s_cmp_lg_u32 s78, 0x100
	s_cbranch_scc1 .Lsg_old_p17
	v_mbcnt_lo_u32_b32 v0, -1, 0
	v_mbcnt_hi_u32_b32 v0, -1, v0
	s_lshr_b32 s1, s84, 6
	s_lshr_b32 s32, s87, 2
	v_and_b32_e32 v1, 15, v0
	v_lshrrev_b32_e32 v2, 4, v0
	s_lshl_b32 s1, s1, 1
	s_add_i32 s1, s1, s32
	s_lshl_b32 s1, s1, 4
	s_add_i32 s1, s1, 0x8000
	v_add_u32_e32 v3, s1, v1
	s_and_b32 s0, s84, 63
	s_lshl_b32 s0, s0, 4
	v_add_u32_e32 v4, s0, v1
	s_and_b32 s32, s87, 3
	s_mul_i32 s32, s32, 0x580
	v_lshl_add_u32 v6, v2, 4, s32
	v_mov_b32_e32 v7, 0
	s_add_u32 s98, s90, 0x14800000
	s_addc_u32 s99, s91, 0
	s_add_u32 s100, s90, 0x2900000
	s_addc_u32 s101, s91, 0
	s_movk_i32 s2, 0x1600
	v_lshl_add_u64 v[8:9], s[98:99], 0, v[6:7]
	v_lshl_add_u64 v[10:11], s[100:101], 0, v[6:7]
	v_mad_u64_u32 v[8:9], vcc, v3, s2, v[8:9]
	v_mad_u64_u32 v[10:11], vcc, v4, s2, v[10:11]
	global_load_dwordx4 v[20:23], v[8:9], off
	global_load_dwordx4 v[108:111], v[10:11], off
	global_load_dwordx4 v[24:27], v[8:9], off offset:64
	global_load_dwordx4 v[112:115], v[10:11], off offset:64
	global_load_dwordx4 v[28:31], v[8:9], off offset:128
	global_load_dwordx4 v[116:119], v[10:11], off offset:128
	global_load_dwordx4 v[32:35], v[8:9], off offset:192
	global_load_dwordx4 v[120:123], v[10:11], off offset:192
	global_load_dwordx4 v[36:39], v[8:9], off offset:256
	global_load_dwordx4 v[124:127], v[10:11], off offset:256
	global_load_dwordx4 v[40:43], v[8:9], off offset:320
	global_load_dwordx4 v[128:131], v[10:11], off offset:320
	global_load_dwordx4 v[44:47], v[8:9], off offset:384
	global_load_dwordx4 v[132:135], v[10:11], off offset:384
	global_load_dwordx4 v[48:51], v[8:9], off offset:448
	global_load_dwordx4 v[136:139], v[10:11], off offset:448
	global_load_dwordx4 v[52:55], v[8:9], off offset:512
	global_load_dwordx4 v[140:143], v[10:11], off offset:512
	global_load_dwordx4 v[56:59], v[8:9], off offset:576
	global_load_dwordx4 v[144:147], v[10:11], off offset:576
	global_load_dwordx4 v[60:63], v[8:9], off offset:640
	global_load_dwordx4 v[148:151], v[10:11], off offset:640
	global_load_dwordx4 v[64:67], v[8:9], off offset:704
	global_load_dwordx4 v[152:155], v[10:11], off offset:704
	global_load_dwordx4 v[68:71], v[8:9], off offset:768
	global_load_dwordx4 v[156:159], v[10:11], off offset:768
	global_load_dwordx4 v[72:75], v[8:9], off offset:832
	global_load_dwordx4 v[160:163], v[10:11], off offset:832
	global_load_dwordx4 v[76:79], v[8:9], off offset:896
	global_load_dwordx4 v[164:167], v[10:11], off offset:896
	global_load_dwordx4 v[80:83], v[8:9], off offset:960
	global_load_dwordx4 v[168:171], v[10:11], off offset:960
	global_load_dwordx4 v[84:87], v[8:9], off offset:1024
	global_load_dwordx4 v[172:175], v[10:11], off offset:1024
	global_load_dwordx4 v[88:91], v[8:9], off offset:1088
	global_load_dwordx4 v[176:179], v[10:11], off offset:1088
	global_load_dwordx4 v[92:95], v[8:9], off offset:1152
	global_load_dwordx4 v[180:183], v[10:11], off offset:1152
	global_load_dwordx4 v[96:99], v[8:9], off offset:1216
	global_load_dwordx4 v[184:187], v[10:11], off offset:1216
	global_load_dwordx4 v[100:103], v[8:9], off offset:1280
	global_load_dwordx4 v[188:191], v[10:11], off offset:1280
	global_load_dwordx4 v[104:107], v[8:9], off offset:1344
	global_load_dwordx4 v[192:195], v[10:11], off offset:1344
	s_lshl_b32 s1, s87, 10
	v_lshl_add_u32 v12, v0, 4, s1
	v_lshlrev_b32_e32 v14, 3, v2
	s_lshl_b32 s1, s0, 1
	v_add_u32_e32 v14, s1, v14
	v_mov_b32_e32 v15, 0
	s_add_u32 s98, s90, 0x8500000
	s_addc_u32 s99, s91, 0
	s_movk_i32 s2, 0x800
	v_lshl_add_u64 v[214:215], s[98:99], 0, v[14:15]
	v_mad_u64_u32 v[214:215], vcc, v3, s2, v[214:215]
	s_waitcnt vmcnt(42)
	v_mfma_f32_16x16x32_bf16 v[196:199], v[108:111], v[20:23], 0
	s_waitcnt vmcnt(40)
	v_mfma_f32_16x16x32_bf16 v[196:199], v[112:115], v[24:27], v[196:199]
	s_waitcnt vmcnt(38)
	v_mfma_f32_16x16x32_bf16 v[196:199], v[116:119], v[28:31], v[196:199]
	s_waitcnt vmcnt(36)
	v_mfma_f32_16x16x32_bf16 v[196:199], v[120:123], v[32:35], v[196:199]
	s_waitcnt vmcnt(34)
	v_mfma_f32_16x16x32_bf16 v[196:199], v[124:127], v[36:39], v[196:199]
	s_waitcnt vmcnt(32)
	v_mfma_f32_16x16x32_bf16 v[196:199], v[128:131], v[40:43], v[196:199]
	s_waitcnt vmcnt(30)
	v_mfma_f32_16x16x32_bf16 v[196:199], v[132:135], v[44:47], v[196:199]
	s_waitcnt vmcnt(28)
	v_mfma_f32_16x16x32_bf16 v[196:199], v[136:139], v[48:51], v[196:199]
	s_waitcnt vmcnt(26)
	v_mfma_f32_16x16x32_bf16 v[196:199], v[140:143], v[52:55], v[196:199]
	s_waitcnt vmcnt(24)
	v_mfma_f32_16x16x32_bf16 v[196:199], v[144:147], v[56:59], v[196:199]
	s_waitcnt vmcnt(22)
	v_mfma_f32_16x16x32_bf16 v[196:199], v[148:151], v[60:63], v[196:199]
	s_waitcnt vmcnt(20)
	v_mfma_f32_16x16x32_bf16 v[196:199], v[152:155], v[64:67], v[196:199]
	s_waitcnt vmcnt(18)
	v_mfma_f32_16x16x32_bf16 v[196:199], v[156:159], v[68:71], v[196:199]
	s_waitcnt vmcnt(16)
	v_mfma_f32_16x16x32_bf16 v[196:199], v[160:163], v[72:75], v[196:199]
	s_waitcnt vmcnt(14)
	v_mfma_f32_16x16x32_bf16 v[196:199], v[164:167], v[76:79], v[196:199]
	s_waitcnt vmcnt(12)
	v_mfma_f32_16x16x32_bf16 v[196:199], v[168:171], v[80:83], v[196:199]
	s_waitcnt vmcnt(10)
	v_mfma_f32_16x16x32_bf16 v[196:199], v[172:175], v[84:87], v[196:199]
	s_waitcnt vmcnt(8)
	v_mfma_f32_16x16x32_bf16 v[196:199], v[176:179], v[88:91], v[196:199]
	s_waitcnt vmcnt(6)
	v_mfma_f32_16x16x32_bf16 v[196:199], v[180:183], v[92:95], v[196:199]
	s_waitcnt vmcnt(4)
	v_mfma_f32_16x16x32_bf16 v[196:199], v[184:187], v[96:99], v[196:199]
	s_waitcnt vmcnt(2)
	v_mfma_f32_16x16x32_bf16 v[196:199], v[188:191], v[100:103], v[196:199]
	s_waitcnt vmcnt(0)
	v_mfma_f32_16x16x32_bf16 v[196:199], v[192:195], v[104:107], v[196:199]
	s_nop 7
	s_nop 1
	ds_write_b128 v12, v[196:199]
	s_waitcnt lgkmcnt(0)
	s_barrier
	s_and_b32 s32, s87, 3
	s_cmp_lg_u32 s32, 0
	s_cbranch_scc1 .Lsg_done_p17
	ds_read_b128 v[200:203], v12 offset:1024
	ds_read_b128 v[204:207], v12 offset:2048
	ds_read_b128 v[208:211], v12 offset:3072
	s_waitcnt lgkmcnt(0)
	v_pk_add_f32 v[196:197], v[196:197], v[200:201]
	v_pk_add_f32 v[198:199], v[198:199], v[202:203]
	v_pk_add_f32 v[204:205], v[204:205], v[208:209]
	v_pk_add_f32 v[206:207], v[206:207], v[210:211]
	v_pk_add_f32 v[196:197], v[196:197], v[204:205]
	v_pk_add_f32 v[198:199], v[198:199], v[206:207]
	v_cvt_pk_bf16_f32 v212, v196, v197
	v_cvt_pk_bf16_f32 v213, v198, v199
	global_store_dwordx2 v[214:215], v[212:213], off

; __global__ void __launch_bounds__(512, 2) mega(Params p) {
	.amdhsa_kernel _Z4mega6Params
		.amdhsa_group_segment_fixed_size 0
		.amdhsa_private_segment_fixed_size 0
		.amdhsa_kernarg_size 488
		.amdhsa_user_sgpr_count 2
		.amdhsa_user_sgpr_dispatch_ptr 0
		.amdhsa_user_sgpr_queue_ptr 0
		.amdhsa_user_sgpr_kernarg_segment_ptr 1
		.amdhsa_user_sgpr_dispatch_id 0
		.amdhsa_user_sgpr_kernarg_preload_length 0
		.amdhsa_user_sgpr_kernarg_preload_offset 0
		.amdhsa_user_sgpr_private_segment_size 0
		.amdhsa_uses_dynamic_stack 0
		.amdhsa_enable_private_segment 0
		.amdhsa_system_sgpr_workgroup_id_x 1
		.amdhsa_system_sgpr_workgroup_id_y 0
		.amdhsa_system_sgpr_workgroup_id_z 0
		.amdhsa_system_sgpr_workgroup_info 0
		.amdhsa_system_vgpr_workitem_id 2
		.amdhsa_next_free_vgpr 255
		.amdhsa_next_free_sgpr 102
		.amdhsa_accum_offset 256
		.amdhsa_reserve_vcc 1
		.amdhsa_float_round_mode_32 0
		.amdhsa_float_round_mode_16_64 0
		.amdhsa_float_denorm_mode_32 3
		.amdhsa_float_denorm_mode_16_64 3
		.amdhsa_dx10_clamp 1
		.amdhsa_ieee_mode 1
		.amdhsa_fp16_overflow 0
		.amdhsa_tg_split 0
		.amdhsa_exception_fp_ieee_invalid_op 0
		.amdhsa_exception_fp_denorm_src 0
		.amdhsa_exception_fp_ieee_div_zero 0
		.amdhsa_exception_fp_ieee_overflow 0
		.amdhsa_exception_fp_ieee_underflow 0
		.amdhsa_exception_fp_ieee_inexact 0
		.amdhsa_exception_int_div_zero 0
	.end_amdhsa_kernel

; __global__ void __launch_bounds__(512, 2) mega(Params p) {
amdhsa.kernels:
  - .agpr_count:     0
    .args:
      - .offset:         0
        .size:           232
        .value_kind:     by_value
      - .offset:         232
        .size:           4
        .value_kind:     hidden_block_count_x
      - .offset:         236
        .size:           4
        .value_kind:     hidden_block_count_y
      - .offset:         240
        .size:           4
        .value_kind:     hidden_block_count_z
      - .offset:         244
        .size:           2
        .value_kind:     hidden_group_size_x
      - .offset:         246
        .size:           2
        .value_kind:     hidden_group_size_y
      - .offset:         248
        .size:           2
        .value_kind:     hidden_group_size_z
      - .offset:         250
        .size:           2
        .value_kind:     hidden_remainder_x
      - .offset:         252
        .size:           2
        .value_kind:     hidden_remainder_y
      - .offset:         254
        .size:           2
        .value_kind:     hidden_remainder_z
      - .offset:         272
        .size:           8
        .value_kind:     hidden_global_offset_x
      - .offset:         280
        .size:           8
        .value_kind:     hidden_global_offset_y
      - .offset:         288
        .size:           8
        .value_kind:     hidden_global_offset_z
      - .offset:         296
        .size:           2
        .value_kind:     hidden_grid_dims
      - .offset:         320
        .size:           8
        .value_kind:     hidden_multigrid_sync_arg
      - .offset:         352
        .size:           4
        .value_kind:     hidden_dynamic_lds_size
    .group_segment_fixed_size: 0
    .kernarg_segment_align: 8
    .kernarg_segment_size: 488
    .language:       OpenCL C
    .language_version:
      - 2
      - 0
    .max_flat_workgroup_size: 512
    .name:           _Z4mega6Params
    .private_segment_fixed_size: 0
    .sgpr_count:     108
    .sgpr_spill_count: 62
    .symbol:         _Z4mega6Params.kd
    .uniform_work_group_size: 1
    .uses_dynamic_stack: false
    .vgpr_count:     255
    .vgpr_spill_count: 0
    .wavefront_size: 64
